# G1 tiles: the 8 row-partial loads of the epilogue are issued at the tile head (before tile-order arithmetic and accumulator clearing) and reduced before the K loop; the epilogue starts with no load an
# speedup vs baseline: 1.0087x; 1.0087x over previous
; template <class EpiT>
; __device__ __forceinline__ void gemm_phase(LAS unsigned char* lds, const Gemm g, const StaticOrder& S, const EpiT& E, int wv) {
;     ...
;     for (;;) {
;         const bool has_next = S.next(ui + 1, nxt);
;         const char* nA = has_next ? (const char*)g.A + (size_t)nxt.pm * tA + (size_t)nxt.pn * g.apn * 2 : cA; const char* nB = has_next ? (const char*)g.Bt + (size_t)nxt.pn * tB : cB;
;     __device__ __forceinline__ void load(Ld& d, int row, int, int, int) const {
; #pragma unroll
;         for (int i = 0; i < 4; ++i) d.p[i] = ((const f32x4*)(ssqh + (size_t)row * 16))[i]; }
.LBB0_261:
	s_cmp_lg_u32 s35, 0
	s_cbranch_scc1 .Lg1pf_skip
	v_lshl_add_u32 v178, s63, 8, v17
	v_lshlrev_b32_e32 v178, 6, v178
	v_and_b32_e32 v179, 0x30, v228
	v_or_b32_e32 v178, v178, v179
	v_add_u32_e32 v179, 0x2000, v178
	global_load_dwordx4 v[134:137], v178, s[24:25]
	global_load_dwordx4 v[138:141], v178, s[24:25] offset:1024
	global_load_dwordx4 v[142:145], v178, s[24:25] offset:2048
	global_load_dwordx4 v[146:149], v178, s[24:25] offset:3072
	global_load_dwordx4 v[154:157], v179, s[24:25]
	global_load_dwordx4 v[160:163], v179, s[24:25] offset:1024
	global_load_dwordx4 v[164:167], v179, s[24:25] offset:2048
	global_load_dwordx4 v[168:171], v179, s[24:25] offset:3072

; template <class EpiT>
; __device__ __forceinline__ void gemm_phase(LAS unsigned char* lds, const Gemm g, const StaticOrder& S, const EpiT& E, int wv) {
;     ...
;     { float z = 0.f; asm volatile("" : "+v"(z));
; #pragma unroll
;     for (int a = 0; a < 2; ++a)
; #pragma unroll
;         for (int b = 0; b < 2; ++b)
; #pragma unroll
;             for (int m = 0; m < 4; ++m)
; #pragma unroll
;                 for (int n = 0; n < 2; ++n) acc[a][b][m][n] = (f32x4){z, z, z, z}; }
;     __device__ __forceinline__ void apply(const Ld& d, int row, int c0, int pn, int wc, int fq, const f32x4& a0, const f32x4& b0, const f32x4& a1, const f32x4& b1) const {
;         const f32x4 t = (d.p[0] + d.p[1]) + (d.p[2] + d.p[3]);
;         const float inv = __builtin_amdgcn_rsqf(((t[0] + t[1]) + (t[2] + t[3])) * (1.f / DM) + EPS);
.LBB0_270:
	s_add_u32 s0, s42, 0x80
	s_addc_u32 s1, s43, 0
	s_add_u32 s40, s40, 0x100
	v_mov_b64_e32 v[8:9], v[4:5]
	v_mov_b64_e32 v[24:25], v[4:5]
	v_mov_b64_e32 v[28:29], v[4:5]
	v_mov_b64_e32 v[40:41], v[4:5]
	v_mov_b64_e32 v[44:45], v[4:5]
	v_mov_b64_e32 v[56:57], v[4:5]
	v_mov_b64_e32 v[60:61], v[4:5]
	v_mov_b64_e32 v[12:13], v[4:5]
	v_mov_b64_e32 v[20:21], v[4:5]
	v_mov_b64_e32 v[32:33], v[4:5]
	v_mov_b64_e32 v[36:37], v[4:5]
	v_mov_b64_e32 v[48:49], v[4:5]
	v_mov_b64_e32 v[52:53], v[4:5]
	v_mov_b64_e32 v[64:65], v[4:5]
	v_mov_b64_e32 v[68:69], v[4:5]
	v_mov_b64_e32 v[72:73], v[4:5]
	v_mov_b64_e32 v[76:77], v[4:5]
	v_mov_b64_e32 v[88:89], v[4:5]
	v_mov_b64_e32 v[92:93], v[4:5]
	v_mov_b64_e32 v[104:105], v[4:5]
	v_mov_b64_e32 v[108:109], v[4:5]
	v_mov_b64_e32 v[120:121], v[4:5]
	v_mov_b64_e32 v[124:125], v[4:5]
	v_mov_b64_e32 v[80:81], v[4:5]
	v_mov_b64_e32 v[84:85], v[4:5]
	v_mov_b64_e32 v[96:97], v[4:5]
	v_mov_b64_e32 v[100:101], v[4:5]
	v_mov_b64_e32 v[112:113], v[4:5]
	v_mov_b64_e32 v[116:117], v[4:5]
	v_mov_b64_e32 v[128:129], v[4:5]
	v_mov_b64_e32 v[132:133], v[4:5]
	s_addc_u32 s41, s41, 0
	s_mov_b32 s22, 0
	v_mov_b64_e32 v[6:7], v[2:3]
	v_mov_b64_e32 v[22:23], v[2:3]
	v_mov_b64_e32 v[26:27], v[2:3]
	v_mov_b64_e32 v[38:39], v[2:3]
	v_mov_b64_e32 v[42:43], v[2:3]
	v_mov_b64_e32 v[54:55], v[2:3]
	v_mov_b64_e32 v[58:59], v[2:3]
	v_mov_b64_e32 v[10:11], v[2:3]
	v_mov_b64_e32 v[18:19], v[2:3]
	v_mov_b64_e32 v[30:31], v[2:3]
	v_mov_b64_e32 v[34:35], v[2:3]
	v_mov_b64_e32 v[46:47], v[2:3]
	v_mov_b64_e32 v[50:51], v[2:3]
	v_mov_b64_e32 v[62:63], v[2:3]
	v_mov_b64_e32 v[66:67], v[2:3]
	v_mov_b64_e32 v[70:71], v[2:3]
	v_mov_b64_e32 v[74:75], v[2:3]
	v_mov_b64_e32 v[86:87], v[2:3]
	v_mov_b64_e32 v[90:91], v[2:3]
	v_mov_b64_e32 v[102:103], v[2:3]
	v_mov_b64_e32 v[106:107], v[2:3]
	v_mov_b64_e32 v[118:119], v[2:3]
	v_mov_b64_e32 v[122:123], v[2:3]
	v_mov_b64_e32 v[78:79], v[2:3]
	v_mov_b64_e32 v[82:83], v[2:3]
	v_mov_b64_e32 v[94:95], v[2:3]
	v_mov_b64_e32 v[98:99], v[2:3]
	v_mov_b64_e32 v[110:111], v[2:3]
	v_mov_b64_e32 v[114:115], v[2:3]
	v_mov_b64_e32 v[126:127], v[2:3]
	v_mov_b64_e32 v[130:131], v[2:3]
	s_cmp_lg_u32 s35, 0
	s_cbranch_scc1 .Lg1rd_skipA
	s_waitcnt vmcnt(0)
	v_add_f32_e32 v204, v134, v135
	v_add_f32_e32 v212, v136, v137
	v_add_f32_e32 v205, v138, v139
	v_add_f32_e32 v213, v140, v141
	v_add_f32_e32 v206, v142, v143
	v_add_f32_e32 v214, v144, v145
	v_add_f32_e32 v207, v146, v147
	v_add_f32_e32 v215, v148, v149
	v_add_f32_e32 v208, v154, v155
	v_add_f32_e32 v216, v156, v157
	v_add_f32_e32 v209, v160, v161
	v_add_f32_e32 v217, v162, v163
	v_add_f32_e32 v210, v164, v165
	v_add_f32_e32 v218, v166, v167
	v_add_f32_e32 v211, v168, v169
	v_add_f32_e32 v219, v170, v171
	v_add_f32_e32 v204, v204, v212
	v_add_f32_e32 v205, v205, v213
	v_add_f32_e32 v206, v206, v214
	v_add_f32_e32 v207, v207, v215
	v_add_f32_e32 v208, v208, v216
	v_add_f32_e32 v209, v209, v217
	v_add_f32_e32 v210, v210, v218
	v_add_f32_e32 v211, v211, v219
	ds_swizzle_b32 v212, v204 offset:swizzle(SWAP,16)
	ds_swizzle_b32 v213, v205 offset:swizzle(SWAP,16)
	ds_swizzle_b32 v214, v206 offset:swizzle(SWAP,16)
	ds_swizzle_b32 v215, v207 offset:swizzle(SWAP,16)
	ds_swizzle_b32 v216, v208 offset:swizzle(SWAP,16)
	ds_swizzle_b32 v217, v209 offset:swizzle(SWAP,16)
	ds_swizzle_b32 v218, v210 offset:swizzle(SWAP,16)
	ds_swizzle_b32 v219, v211 offset:swizzle(SWAP,16)
	s_waitcnt lgkmcnt(0)
	v_add_f32_e32 v204, v204, v212
	v_add_f32_e32 v205, v205, v213
	v_add_f32_e32 v206, v206, v214
	v_add_f32_e32 v207, v207, v215
	v_add_f32_e32 v208, v208, v216
	v_add_f32_e32 v209, v209, v217
	v_add_f32_e32 v210, v210, v218
	v_add_f32_e32 v211, v211, v219
	v_mov_b32_e32 v212, v204
	v_mov_b32_e32 v213, v205
	v_mov_b32_e32 v214, v206
	v_mov_b32_e32 v215, v207
	v_mov_b32_e32 v216, v208
	v_mov_b32_e32 v217, v209
	v_mov_b32_e32 v218, v210
	v_mov_b32_e32 v219, v211
	s_nop 1
	v_permlane32_swap_b32_e32 v204, v212
	v_permlane32_swap_b32_e32 v205, v213
	v_permlane32_swap_b32_e32 v206, v214
	v_permlane32_swap_b32_e32 v207, v215
	v_permlane32_swap_b32_e32 v208, v216
	v_permlane32_swap_b32_e32 v209, v217
	v_permlane32_swap_b32_e32 v210, v218
	v_permlane32_swap_b32_e32 v211, v219
	v_add_f32_e32 v183, v204, v212
	v_add_f32_e32 v185, v205, v213
	v_add_f32_e32 v187, v206, v214
	v_add_f32_e32 v197, v207, v215
	v_add_f32_e32 v199, v208, v216
	v_add_f32_e32 v201, v209, v217
	v_add_f32_e32 v203, v210, v218
	v_add_f32_e32 v230, v211, v219
	v_fmamk_f32 v183, v183, 0x3a800000, v229
	v_fmamk_f32 v185, v185, 0x3a800000, v229
	v_fmamk_f32 v187, v187, 0x3a800000, v229
	v_fmamk_f32 v197, v197, 0x3a800000, v229
	v_fmamk_f32 v199, v199, 0x3a800000, v229
	v_fmamk_f32 v201, v201, 0x3a800000, v229
	v_fmamk_f32 v203, v203, 0x3a800000, v229
	v_fmamk_f32 v230, v230, 0x3a800000, v229
	v_rsq_f32_e32 v183, v183
	v_rsq_f32_e32 v185, v185
	v_rsq_f32_e32 v187, v187
	v_rsq_f32_e32 v197, v197
	v_rsq_f32_e32 v199, v199
	v_rsq_f32_e32 v201, v201
	v_rsq_f32_e32 v203, v203
	v_rsq_f32_e32 v230, v230
; #define PG8_STAGE(bufoff, gbase, voff) do { _Pragma("unroll") for (int _i = 0; _i < 2; ++_i) \
;         __builtin_amdgcn_global_load_lds((const unsigned*)((const char*)(gbase) + (voff)[_i]), (LAS unsigned*)(lds + (bufoff) + ldsw + _i * 8192), 16, 0, 0); } while (0)
; #define PG8_LDA(dst, b, h) do { _Pragma("unroll") for (int m = 0; m < 4; ++m) _Pragma("unroll") for (int k = 0; k < 2; ++k) dst[m][k] = *(const LAS bf16x8*)(lds + PG8_SA(b, h) + aoff + m * 2048 + k * 1024); } while (0)
; #define PG8_LDB(dst, b, h) do { _Pragma("unroll") for (int n = 0; n < 2; ++n) _Pragma("unroll") for (int k = 0; k < 2; ++k) dst[n][k] = *(const LAS bf16x8*)(lds + PG8_SB(b, h) + boff + n * 2048 + k * 1024); } while (0)
; #define PG8_MMA(ai, bj, At, Bt) do { __builtin_amdgcn_s_setprio(1); _Pragma("unroll") for (int m = 0; m < 4; ++m) _Pragma("unroll") for (int n = 0; n < 2; ++n) _Pragma("unroll") for (int k = 0; k < 2; ++k) \
;         acc[ai][bj][m][n] = __builtin_amdgcn_mfma_f32_16x16x32_bf16(Bt[n][k], At[m][k], acc[ai][bj][m][n], 0, 0, 0); __builtin_amdgcn_s_setprio(0); } while (0)
; #define PG8_WAIT_V(n) asm volatile("s_waitcnt vmcnt(" #n ")" ::: "memory")
; #define PG8_WAIT_L(n) asm volatile("s_waitcnt lgkmcnt(" #n ")" ::: "memory")
; #define PG8_BAR __builtin_amdgcn_s_barrier()
; #define PG8_SCHED __builtin_amdgcn_sched_barrier(0)
; template <class EpiT>
; __device__ __forceinline__ void gemm_phase(LAS unsigned char* lds, const Gemm g, const StaticOrder& S, const EpiT& E, int wv) {
;     ...
;             PG8_LDB(B0, 0, 0); PG8_LDB(B1, 0, 1); PG8_SCHED; PG8_LDA(At, 0, 0); PG8_STAGE(PG8_SA(1, 1), a1 + hA, voffA);
;             PG8_WAIT_V(8); PG8_WAIT_L(0); PG8_BAR; PG8_MMA(0, 0, At, B0); PG8_MMA(0, 1, At, B1); PG8_BAR; PG8_SCHED;
;             PG8_LDA(At, 0, 1); PG8_STAGE(PG8_SB(0, 0), b2, voffB); PG8_STAGE(PG8_SB(0, 1), b2 + hB, voffB); PG8_STAGE(PG8_SA(0, 0), a2, voffA);
;             PG8_WAIT_V(8); PG8_WAIT_L(0); PG8_BAR; PG8_MMA(1, 0, At, B0); PG8_MMA(1, 1, At, B1); PG8_BAR; PG8_SCHED;
;             PG8_LDB(B0, 1, 0); PG8_LDB(B1, 1, 1); PG8_SCHED; PG8_LDA(At, 1, 0); PG8_STAGE(PG8_SA(0, 1), a2 + hA, voffA);
;             PG8_WAIT_V(8); PG8_WAIT_L(0); PG8_BAR; PG8_MMA(0, 0, At, B0); PG8_MMA(0, 1, At, B1); PG8_BAR; PG8_SCHED;
.Lg1rd_skipA:
.LBB0_271:
	s_add_i32 s42, s22, 2
	s_add_u32 s43, s0, 0x80
	s_addc_u32 s23, s1, 0
	s_add_i32 s64, 0, 0x10000
	s_cmp_eq_u32 s52, s22
	s_cselect_b32 s23, s19, s23
	s_cselect_b32 s22, s18, s43
	v_add_u32_e32 v0, s64, v234
	s_cselect_b32 s45, s21, s41
	s_cselect_b32 s44, s20, s40
	s_add_i32 s43, 0, 0x14000
	ds_read_b128 v[134:137], v0
	ds_read_b128 v[138:141], v0 offset:1024
	ds_read_b128 v[142:145], v0 offset:2048
	ds_read_b128 v[146:149], v0 offset:3072
	v_add_u32_e32 v0, s43, v234
	ds_read_b128 v[150:153], v0
	ds_read_b128 v[154:157], v0 offset:1024
	ds_read_b128 v[158:161], v0 offset:2048
	ds_read_b128 v[162:165], v0 offset:3072
	s_add_i32 m0, s14, 0xc000
	ds_read_b128 v[166:169], v242
	ds_read_b128 v[170:173], v242 offset:1024
	ds_read_b128 v[174:177], v242 offset:2048
	ds_read_b128 v[178:181], v242 offset:3072
	ds_read_b128 v[204:207], v242 offset:4096
	ds_read_b128 v[208:211], v242 offset:5120
	ds_read_b128 v[212:215], v242 offset:6144
	ds_read_b128 v[216:219], v242 offset:7168
	global_load_lds_dwordx4 v196, s[0:1]
	s_add_i32 m0, s14, 0xe000
	s_nop 0
	global_load_lds_dwordx4 v198, s[0:1]
	s_waitcnt vmcnt(8)
	s_waitcnt lgkmcnt(0)
	s_barrier
	s_setprio 1
	s_waitcnt lgkmcnt(0)
	v_mfma_f32_16x16x32_bf16 v[130:133], v[134:137], v[166:169], v[130:133]
	v_mfma_f32_16x16x32_bf16 v[126:129], v[142:145], v[166:169], v[126:129]
	v_mfma_f32_16x16x32_bf16 v[114:117], v[134:137], v[174:177], v[114:117]
	v_mfma_f32_16x16x32_bf16 v[110:113], v[142:145], v[174:177], v[110:113]
	v_mfma_f32_16x16x32_bf16 v[98:101], v[134:137], v[204:207], v[98:101]
	v_mfma_f32_16x16x32_bf16 v[94:97], v[142:145], v[204:207], v[94:97]
	v_mfma_f32_16x16x32_bf16 v[82:85], v[134:137], v[212:215], v[82:85]
	v_mfma_f32_16x16x32_bf16 v[78:81], v[142:145], v[212:215], v[78:81]
	v_mfma_f32_16x16x32_bf16 v[130:133], v[138:141], v[170:173], v[130:133]
	v_mfma_f32_16x16x32_bf16 v[126:129], v[146:149], v[170:173], v[126:129]
	v_mfma_f32_16x16x32_bf16 v[114:117], v[138:141], v[178:181], v[114:117]
	v_mfma_f32_16x16x32_bf16 v[110:113], v[146:149], v[178:181], v[110:113]
	v_mfma_f32_16x16x32_bf16 v[98:101], v[138:141], v[208:211], v[98:101]
	v_mfma_f32_16x16x32_bf16 v[94:97], v[146:149], v[208:211], v[94:97]
	v_mfma_f32_16x16x32_bf16 v[82:85], v[138:141], v[216:219], v[82:85]
	v_mfma_f32_16x16x32_bf16 v[78:81], v[146:149], v[216:219], v[78:81]
	s_setprio 0
	s_setprio 1
	v_mfma_f32_16x16x32_bf16 v[122:125], v[150:153], v[166:169], v[122:125]
	v_mfma_f32_16x16x32_bf16 v[118:121], v[158:161], v[166:169], v[118:121]
	v_mfma_f32_16x16x32_bf16 v[106:109], v[150:153], v[174:177], v[106:109]
	v_mfma_f32_16x16x32_bf16 v[102:105], v[158:161], v[174:177], v[102:105]
	v_mfma_f32_16x16x32_bf16 v[90:93], v[150:153], v[204:207], v[90:93]
	v_mfma_f32_16x16x32_bf16 v[86:89], v[158:161], v[204:207], v[86:89]
	v_mfma_f32_16x16x32_bf16 v[74:77], v[150:153], v[212:215], v[74:77]
	v_mfma_f32_16x16x32_bf16 v[70:73], v[158:161], v[212:215], v[70:73]
	v_mfma_f32_16x16x32_bf16 v[122:125], v[154:157], v[170:173], v[122:125]
	v_mfma_f32_16x16x32_bf16 v[118:121], v[162:165], v[170:173], v[118:121]
	v_mfma_f32_16x16x32_bf16 v[106:109], v[154:157], v[178:181], v[106:109]
	v_mfma_f32_16x16x32_bf16 v[102:105], v[162:165], v[178:181], v[102:105]
	v_mfma_f32_16x16x32_bf16 v[90:93], v[154:157], v[208:211], v[90:93]
	v_mfma_f32_16x16x32_bf16 v[86:89], v[162:165], v[208:211], v[86:89]
	v_mfma_f32_16x16x32_bf16 v[74:77], v[154:157], v[216:219], v[74:77]
	v_mfma_f32_16x16x32_bf16 v[70:73], v[162:165], v[216:219], v[70:73]
	s_setprio 0
	s_barrier
	s_add_i32 s64, s64, s13
	s_mov_b32 m0, s64
	s_add_u32 s36, s44, 0x80
	s_addc_u32 s37, s45, 0
	ds_read_b128 v[166:169], v242 offset:16384
	ds_read_b128 v[170:173], v242 offset:17408
	ds_read_b128 v[174:177], v242 offset:18432
	ds_read_b128 v[178:181], v242 offset:19456
	ds_read_b128 v[204:207], v242 offset:20480
	ds_read_b128 v[208:211], v242 offset:21504
	ds_read_b128 v[212:215], v242 offset:22528
	ds_read_b128 v[216:219], v242 offset:23552
	global_load_lds_dwordx4 v182, s[44:45]
	s_add_i32 m0, s64, 0x2000
	s_add_i32 s43, s43, s13
	global_load_lds_dwordx4 v186, s[44:45]
	s_add_u32 s44, s44, s8
	s_addc_u32 s45, s45, 0
	s_mov_b32 m0, s43
	s_add_u32 s38, s44, 0x80
	s_addc_u32 s39, s45, 0
	global_load_lds_dwordx4 v182, s[44:45]
	s_add_i32 m0, s43, 0x2000
	s_add_u32 s46, s22, 0x80
	s_addc_u32 s47, s23, 0
	global_load_lds_dwordx4 v186, s[44:45]
	s_mov_b32 m0, s14
	s_nop 0
	global_load_lds_dwordx4 v14, s[22:23]
	s_mov_b32 m0, s15
	s_nop 0
	global_load_lds_dwordx4 v184, s[22:23]
	s_waitcnt vmcnt(8)
	s_waitcnt lgkmcnt(0)
	s_barrier
; #define PG8_STAGE(bufoff, gbase, voff) do { _Pragma("unroll") for (int _i = 0; _i < 2; ++_i) \
;         __builtin_amdgcn_global_load_lds((const unsigned*)((const char*)(gbase) + (voff)[_i]), (LAS unsigned*)(lds + (bufoff) + ldsw + _i * 8192), 16, 0, 0); } while (0)
; #define PG8_LDA(dst, b, h) do { _Pragma("unroll") for (int m = 0; m < 4; ++m) _Pragma("unroll") for (int k = 0; k < 2; ++k) dst[m][k] = *(const LAS bf16x8*)(lds + PG8_SA(b, h) + aoff + m * 2048 + k * 1024); } while (0)
; #define PG8_LDB(dst, b, h) do { _Pragma("unroll") for (int n = 0; n < 2; ++n) _Pragma("unroll") for (int k = 0; k < 2; ++k) dst[n][k] = *(const LAS bf16x8*)(lds + PG8_SB(b, h) + boff + n * 2048 + k * 1024); } while (0)
; #define PG8_MMA(ai, bj, At, Bt) do { __builtin_amdgcn_s_setprio(1); _Pragma("unroll") for (int m = 0; m < 4; ++m) _Pragma("unroll") for (int n = 0; n < 2; ++n) _Pragma("unroll") for (int k = 0; k < 2; ++k) \
;         acc[ai][bj][m][n] = __builtin_amdgcn_mfma_f32_16x16x32_bf16(Bt[n][k], At[m][k], acc[ai][bj][m][n], 0, 0, 0); __builtin_amdgcn_s_setprio(0); } while (0)
; #define PG8_WAIT_V(n) asm volatile("s_waitcnt vmcnt(" #n ")" ::: "memory")
; #define PG8_WAIT_L(n) asm volatile("s_waitcnt lgkmcnt(" #n ")" ::: "memory")
; #define PG8_BAR __builtin_amdgcn_s_barrier()
; #define PG8_SCHED __builtin_amdgcn_sched_barrier(0)
; template <class EpiT>
; __device__ __forceinline__ void gemm_phase(LAS unsigned char* lds, const Gemm g, const StaticOrder& S, const EpiT& E, int wv) {
;     ...
;             PG8_WAIT_V(8); PG8_WAIT_L(0); PG8_BAR; PG8_MMA(1, 0, At, B0); PG8_MMA(1, 1, At, B1); PG8_BAR; PG8_SCHED;
;             PG8_LDB(B0, 1, 0); PG8_LDB(B1, 1, 1); PG8_SCHED; PG8_LDA(At, 1, 0); PG8_STAGE(PG8_SA(0, 1), a2 + hA, voffA);
;             PG8_WAIT_V(8); PG8_WAIT_L(0); PG8_BAR; PG8_MMA(0, 0, At, B0); PG8_MMA(0, 1, At, B1); PG8_BAR; PG8_SCHED;
	s_setprio 1
	s_waitcnt lgkmcnt(0)
	v_mfma_f32_16x16x32_bf16 v[66:69], v[134:137], v[166:169], v[66:69]
	v_mfma_f32_16x16x32_bf16 v[62:65], v[142:145], v[166:169], v[62:65]
	v_mfma_f32_16x16x32_bf16 v[50:53], v[134:137], v[174:177], v[50:53]
	v_mfma_f32_16x16x32_bf16 v[46:49], v[142:145], v[174:177], v[46:49]
	v_mfma_f32_16x16x32_bf16 v[34:37], v[134:137], v[204:207], v[34:37]
	v_mfma_f32_16x16x32_bf16 v[30:33], v[142:145], v[204:207], v[30:33]
	v_mfma_f32_16x16x32_bf16 v[18:21], v[134:137], v[212:215], v[18:21]
	v_mfma_f32_16x16x32_bf16 v[10:13], v[142:145], v[212:215], v[10:13]
	v_mfma_f32_16x16x32_bf16 v[66:69], v[138:141], v[170:173], v[66:69]
	v_mfma_f32_16x16x32_bf16 v[62:65], v[146:149], v[170:173], v[62:65]
	v_mfma_f32_16x16x32_bf16 v[50:53], v[138:141], v[178:181], v[50:53]
	v_mfma_f32_16x16x32_bf16 v[46:49], v[146:149], v[178:181], v[46:49]
	v_mfma_f32_16x16x32_bf16 v[34:37], v[138:141], v[208:211], v[34:37]
	v_mfma_f32_16x16x32_bf16 v[30:33], v[146:149], v[208:211], v[30:33]
	v_mfma_f32_16x16x32_bf16 v[18:21], v[138:141], v[216:219], v[18:21]
	v_mfma_f32_16x16x32_bf16 v[10:13], v[146:149], v[216:219], v[10:13]
	s_setprio 0
	s_setprio 1
	v_mfma_f32_16x16x32_bf16 v[58:61], v[150:153], v[166:169], v[58:61]
	v_mfma_f32_16x16x32_bf16 v[54:57], v[158:161], v[166:169], v[54:57]
	v_mfma_f32_16x16x32_bf16 v[42:45], v[150:153], v[174:177], v[42:45]
	v_mfma_f32_16x16x32_bf16 v[38:41], v[158:161], v[174:177], v[38:41]
	v_mfma_f32_16x16x32_bf16 v[26:29], v[150:153], v[204:207], v[26:29]
	v_mfma_f32_16x16x32_bf16 v[22:25], v[158:161], v[204:207], v[22:25]
	v_mfma_f32_16x16x32_bf16 v[6:9], v[150:153], v[212:215], v[6:9]
	v_mfma_f32_16x16x32_bf16 v[2:5], v[158:161], v[212:215], v[2:5]
	v_mfma_f32_16x16x32_bf16 v[58:61], v[154:157], v[170:173], v[58:61]
	v_mfma_f32_16x16x32_bf16 v[54:57], v[162:165], v[170:173], v[54:57]
	v_mfma_f32_16x16x32_bf16 v[42:45], v[154:157], v[178:181], v[42:45]
	v_mfma_f32_16x16x32_bf16 v[38:41], v[162:165], v[178:181], v[38:41]
	v_mfma_f32_16x16x32_bf16 v[26:29], v[154:157], v[208:211], v[26:29]
	v_mfma_f32_16x16x32_bf16 v[22:25], v[162:165], v[208:211], v[22:25]
	v_mfma_f32_16x16x32_bf16 v[6:9], v[154:157], v[216:219], v[6:9]
	v_mfma_f32_16x16x32_bf16 v[2:5], v[162:165], v[216:219], v[2:5]
	s_setprio 0
	s_barrier
	s_add_i32 s43, 0, 0x18000
	v_add_u32_e32 v0, s43, v234
	s_add_i32 s44, 0, 0x1c000
	ds_read_b128 v[134:137], v0
	ds_read_b128 v[138:141], v0 offset:1024
	ds_read_b128 v[142:145], v0 offset:2048
	ds_read_b128 v[146:149], v0 offset:3072
	v_add_u32_e32 v0, s44, v234
	ds_read_b128 v[150:153], v0
	ds_read_b128 v[154:157], v0 offset:1024
	ds_read_b128 v[158:161], v0 offset:2048
	ds_read_b128 v[162:165], v0 offset:3072
	s_add_u32 s22, s22, s4
	s_addc_u32 s23, s23, 0
	s_mov_b32 m0, s88
	ds_read_b128 v[166:169], v242 offset:32768
	ds_read_b128 v[170:173], v242 offset:33792
	ds_read_b128 v[174:177], v242 offset:34816
	ds_read_b128 v[178:181], v242 offset:35840
	ds_read_b128 v[204:207], v242 offset:36864
	ds_read_b128 v[208:211], v242 offset:37888
	ds_read_b128 v[212:215], v242 offset:38912
	ds_read_b128 v[216:219], v242 offset:39936
	global_load_lds_dwordx4 v14, s[22:23]
	s_mov_b32 m0, s89
	s_nop 0
	global_load_lds_dwordx4 v184, s[22:23]
	s_waitcnt vmcnt(8)
	s_waitcnt lgkmcnt(0)
	s_barrier
	s_setprio 1
	s_waitcnt lgkmcnt(0)
	v_mfma_f32_16x16x32_bf16 v[130:133], v[134:137], v[166:169], v[130:133]
	v_mfma_f32_16x16x32_bf16 v[126:129], v[142:145], v[166:169], v[126:129]
	v_mfma_f32_16x16x32_bf16 v[114:117], v[134:137], v[174:177], v[114:117]
	v_mfma_f32_16x16x32_bf16 v[110:113], v[142:145], v[174:177], v[110:113]
	v_mfma_f32_16x16x32_bf16 v[98:101], v[134:137], v[204:207], v[98:101]
	v_mfma_f32_16x16x32_bf16 v[94:97], v[142:145], v[204:207], v[94:97]
	v_mfma_f32_16x16x32_bf16 v[82:85], v[134:137], v[212:215], v[82:85]
	v_mfma_f32_16x16x32_bf16 v[78:81], v[142:145], v[212:215], v[78:81]
	v_mfma_f32_16x16x32_bf16 v[130:133], v[138:141], v[170:173], v[130:133]
	v_mfma_f32_16x16x32_bf16 v[126:129], v[146:149], v[170:173], v[126:129]
	v_mfma_f32_16x16x32_bf16 v[114:117], v[138:141], v[178:181], v[114:117]
	v_mfma_f32_16x16x32_bf16 v[110:113], v[146:149], v[178:181], v[110:113]
	v_mfma_f32_16x16x32_bf16 v[98:101], v[138:141], v[208:211], v[98:101]
	v_mfma_f32_16x16x32_bf16 v[94:97], v[146:149], v[208:211], v[94:97]
	v_mfma_f32_16x16x32_bf16 v[82:85], v[138:141], v[216:219], v[82:85]
	v_mfma_f32_16x16x32_bf16 v[78:81], v[146:149], v[216:219], v[78:81]
	s_setprio 0
	s_setprio 1
	v_mfma_f32_16x16x32_bf16 v[122:125], v[150:153], v[166:169], v[122:125]
	v_mfma_f32_16x16x32_bf16 v[118:121], v[158:161], v[166:169], v[118:121]
	v_mfma_f32_16x16x32_bf16 v[106:109], v[150:153], v[174:177], v[106:109]
	v_mfma_f32_16x16x32_bf16 v[102:105], v[158:161], v[174:177], v[102:105]
	v_mfma_f32_16x16x32_bf16 v[90:93], v[150:153], v[204:207], v[90:93]
	v_mfma_f32_16x16x32_bf16 v[86:89], v[158:161], v[204:207], v[86:89]
	v_mfma_f32_16x16x32_bf16 v[74:77], v[150:153], v[212:215], v[74:77]
	v_mfma_f32_16x16x32_bf16 v[70:73], v[158:161], v[212:215], v[70:73]
	v_mfma_f32_16x16x32_bf16 v[122:125], v[154:157], v[170:173], v[122:125]
	v_mfma_f32_16x16x32_bf16 v[118:121], v[162:165], v[170:173], v[118:121]
	v_mfma_f32_16x16x32_bf16 v[106:109], v[154:157], v[178:181], v[106:109]
	v_mfma_f32_16x16x32_bf16 v[102:105], v[162:165], v[178:181], v[102:105]
	v_mfma_f32_16x16x32_bf16 v[90:93], v[154:157], v[208:211], v[90:93]
	v_mfma_f32_16x16x32_bf16 v[86:89], v[162:165], v[208:211], v[86:89]
	v_mfma_f32_16x16x32_bf16 v[74:77], v[154:157], v[216:219], v[74:77]
	v_mfma_f32_16x16x32_bf16 v[70:73], v[162:165], v[216:219], v[70:73]
	s_setprio 0
	s_barrier
; #define PG8_STAGE(bufoff, gbase, voff) do { _Pragma("unroll") for (int _i = 0; _i < 2; ++_i) \
;         __builtin_amdgcn_global_load_lds((const unsigned*)((const char*)(gbase) + (voff)[_i]), (LAS unsigned*)(lds + (bufoff) + ldsw + _i * 8192), 16, 0, 0); } while (0)
; #define PG8_LDA(dst, b, h) do { _Pragma("unroll") for (int m = 0; m < 4; ++m) _Pragma("unroll") for (int k = 0; k < 2; ++k) dst[m][k] = *(const LAS bf16x8*)(lds + PG8_SA(b, h) + aoff + m * 2048 + k * 1024); } while (0)
; #define PG8_MMA(ai, bj, At, Bt) do { __builtin_amdgcn_s_setprio(1); _Pragma("unroll") for (int m = 0; m < 4; ++m) _Pragma("unroll") for (int n = 0; n < 2; ++n) _Pragma("unroll") for (int k = 0; k < 2; ++k) \
;         acc[ai][bj][m][n] = __builtin_amdgcn_mfma_f32_16x16x32_bf16(Bt[n][k], At[m][k], acc[ai][bj][m][n], 0, 0, 0); __builtin_amdgcn_s_setprio(0); } while (0)
; #define PG8_WAIT_V(n) asm volatile("s_waitcnt vmcnt(" #n ")" ::: "memory")
; #define PG8_WAIT_L(n) asm volatile("s_waitcnt lgkmcnt(" #n ")" ::: "memory")
; #define PG8_BAR __builtin_amdgcn_s_barrier()
; #define PG8_SCHED __builtin_amdgcn_sched_barrier(0)
; template <class EpiT>
; __device__ __forceinline__ void gemm_phase(LAS unsigned char* lds, const Gemm g, const StaticOrder& S, const EpiT& E, int wv) {
;     ...
;             PG8_LDA(At, 1, 1); PG8_STAGE(PG8_SB(1, 0), b3, voffB); PG8_STAGE(PG8_SB(1, 1), b3 + hB, voffB); PG8_STAGE(PG8_SA(1, 0), a3, voffA);
;             PG8_WAIT_V(8); PG8_WAIT_L(0); PG8_BAR; PG8_MMA(1, 0, At, B0); PG8_MMA(1, 1, At, B1); PG8_BAR; PG8_SCHED;
;         }
	s_add_i32 s22, s43, s13
	s_mov_b32 m0, s22
	ds_read_b128 v[166:169], v242 offset:49152
	ds_read_b128 v[170:173], v242 offset:50176
	ds_read_b128 v[174:177], v242 offset:51200
	ds_read_b128 v[178:181], v242 offset:52224
	ds_read_b128 v[204:207], v242 offset:53248
	ds_read_b128 v[208:211], v242 offset:54272
	ds_read_b128 v[212:215], v242 offset:55296
	ds_read_b128 v[216:219], v242 offset:56320
	global_load_lds_dwordx4 v182, s[36:37]
	s_add_i32 m0, s22, 0x2000
	s_add_i32 s22, s44, s13
	global_load_lds_dwordx4 v186, s[36:37]
	s_mov_b32 m0, s22
	s_nop 0
	global_load_lds_dwordx4 v182, s[38:39]
	s_add_i32 m0, s22, 0x2000
	s_nop 0
	global_load_lds_dwordx4 v186, s[38:39]
	s_mov_b32 m0, s72
	s_nop 0
	global_load_lds_dwordx4 v14, s[46:47]
	s_mov_b32 m0, s73
	s_nop 0
	global_load_lds_dwordx4 v184, s[46:47]
	s_waitcnt vmcnt(8)
	s_waitcnt lgkmcnt(0)
	s_barrier
	s_setprio 1
	s_waitcnt lgkmcnt(0)
	v_mfma_f32_16x16x32_bf16 v[66:69], v[134:137], v[166:169], v[66:69]
	v_mfma_f32_16x16x32_bf16 v[62:65], v[142:145], v[166:169], v[62:65]
	v_mfma_f32_16x16x32_bf16 v[50:53], v[134:137], v[174:177], v[50:53]
	v_mfma_f32_16x16x32_bf16 v[46:49], v[142:145], v[174:177], v[46:49]
	v_mfma_f32_16x16x32_bf16 v[34:37], v[134:137], v[204:207], v[34:37]
	v_mfma_f32_16x16x32_bf16 v[30:33], v[142:145], v[204:207], v[30:33]
	v_mfma_f32_16x16x32_bf16 v[18:21], v[134:137], v[212:215], v[18:21]
	v_mfma_f32_16x16x32_bf16 v[10:13], v[142:145], v[212:215], v[10:13]
	v_mfma_f32_16x16x32_bf16 v[66:69], v[138:141], v[170:173], v[66:69]
	v_mfma_f32_16x16x32_bf16 v[62:65], v[146:149], v[170:173], v[62:65]
	v_mfma_f32_16x16x32_bf16 v[50:53], v[138:141], v[178:181], v[50:53]
	v_mfma_f32_16x16x32_bf16 v[46:49], v[146:149], v[178:181], v[46:49]
	v_mfma_f32_16x16x32_bf16 v[34:37], v[138:141], v[208:211], v[34:37]
	v_mfma_f32_16x16x32_bf16 v[30:33], v[146:149], v[208:211], v[30:33]
	v_mfma_f32_16x16x32_bf16 v[18:21], v[138:141], v[216:219], v[18:21]
	v_mfma_f32_16x16x32_bf16 v[10:13], v[146:149], v[216:219], v[10:13]
	s_setprio 0
	s_setprio 1
	v_mfma_f32_16x16x32_bf16 v[58:61], v[150:153], v[166:169], v[58:61]
	v_mfma_f32_16x16x32_bf16 v[54:57], v[158:161], v[166:169], v[54:57]
	v_mfma_f32_16x16x32_bf16 v[42:45], v[150:153], v[174:177], v[42:45]
	v_mfma_f32_16x16x32_bf16 v[38:41], v[158:161], v[174:177], v[38:41]
	v_mfma_f32_16x16x32_bf16 v[26:29], v[150:153], v[204:207], v[26:29]
	v_mfma_f32_16x16x32_bf16 v[22:25], v[158:161], v[204:207], v[22:25]
	v_mfma_f32_16x16x32_bf16 v[6:9], v[150:153], v[212:215], v[6:9]
	v_mfma_f32_16x16x32_bf16 v[2:5], v[158:161], v[212:215], v[2:5]
	v_mfma_f32_16x16x32_bf16 v[58:61], v[154:157], v[170:173], v[58:61]
	v_mfma_f32_16x16x32_bf16 v[54:57], v[162:165], v[170:173], v[54:57]
	v_mfma_f32_16x16x32_bf16 v[42:45], v[154:157], v[178:181], v[42:45]
	v_mfma_f32_16x16x32_bf16 v[38:41], v[162:165], v[178:181], v[38:41]
	v_mfma_f32_16x16x32_bf16 v[26:29], v[154:157], v[208:211], v[26:29]
	v_mfma_f32_16x16x32_bf16 v[22:25], v[162:165], v[208:211], v[22:25]
	v_mfma_f32_16x16x32_bf16 v[6:9], v[154:157], v[216:219], v[6:9]
	v_mfma_f32_16x16x32_bf16 v[2:5], v[162:165], v[216:219], v[2:5]
	s_setprio 0
	s_barrier
	s_add_u32 s0, s0, 0x100
	s_addc_u32 s1, s1, 0
	s_add_u32 s40, s40, 0x100
	s_addc_u32 s41, s41, 0
	s_cmp_ge_i32 s42, s81
	s_mov_b32 s22, s42
	s_cbranch_scc0 .LBB0_271
	s_and_b64 vcc, exec, s[16:17]
	s_cbranch_vccnz .LBB0_278

; template <class EpiT>
; __device__ __forceinline__ void gemm_phase(LAS unsigned char* lds, const Gemm g, const StaticOrder& S, const EpiT& E, int wv) {
;     ...
;         { float z = 0.f; asm volatile("" : "+v"(z));
; #pragma unroll
;         for (int a = 0; a < 2; ++a)
; #pragma unroll
;             for (int b = 0; b < 2; ++b)
; #pragma unroll
;                 for (int m = 0; m < 4; ++m)
; #pragma unroll
;                     for (int n = 0; n < 2; ++n) acc[a][b][m][n] = (f32x4){z, z, z, z}; }
;     __device__ __forceinline__ void apply(const Ld& d, int row, int c0, int pn, int wc, int fq, const f32x4& a0, const f32x4& b0, const f32x4& a1, const f32x4& b1) const {
;         const f32x4 t = (d.p[0] + d.p[1]) + (d.p[2] + d.p[3]);
;         const float inv = __builtin_amdgcn_rsqf(((t[0] + t[1]) + (t[2] + t[3])) * (1.f / DM) + EPS);
.LBB0_277:
	v_mov_b64_e32 v[132:133], v[4:5]
	v_mov_b64_e32 v[128:129], v[4:5]
	v_mov_b64_e32 v[116:117], v[4:5]
	v_mov_b64_e32 v[112:113], v[4:5]
	v_mov_b64_e32 v[100:101], v[4:5]
	v_mov_b64_e32 v[96:97], v[4:5]
	v_mov_b64_e32 v[84:85], v[4:5]
	v_mov_b64_e32 v[80:81], v[4:5]
	v_mov_b64_e32 v[124:125], v[4:5]
	v_mov_b64_e32 v[120:121], v[4:5]
	v_mov_b64_e32 v[108:109], v[4:5]
	v_mov_b64_e32 v[104:105], v[4:5]
	v_mov_b64_e32 v[92:93], v[4:5]
	v_mov_b64_e32 v[88:89], v[4:5]
	v_mov_b64_e32 v[76:77], v[4:5]
	v_mov_b64_e32 v[72:73], v[4:5]
	v_mov_b64_e32 v[68:69], v[4:5]
	v_mov_b64_e32 v[64:65], v[4:5]
	v_mov_b64_e32 v[52:53], v[4:5]
	v_mov_b64_e32 v[48:49], v[4:5]
	v_mov_b64_e32 v[36:37], v[4:5]
	v_mov_b64_e32 v[32:33], v[4:5]
	v_mov_b64_e32 v[20:21], v[4:5]
	v_mov_b64_e32 v[12:13], v[4:5]
	v_mov_b64_e32 v[60:61], v[4:5]
	v_mov_b64_e32 v[56:57], v[4:5]
	v_mov_b64_e32 v[44:45], v[4:5]
	v_mov_b64_e32 v[40:41], v[4:5]
	v_mov_b64_e32 v[28:29], v[4:5]
	v_mov_b64_e32 v[24:25], v[4:5]
	v_mov_b64_e32 v[8:9], v[4:5]
	v_mov_b64_e32 v[130:131], v[2:3]
	v_mov_b64_e32 v[126:127], v[2:3]
	v_mov_b64_e32 v[114:115], v[2:3]
	v_mov_b64_e32 v[110:111], v[2:3]
	v_mov_b64_e32 v[98:99], v[2:3]
	v_mov_b64_e32 v[94:95], v[2:3]
	v_mov_b64_e32 v[82:83], v[2:3]
	v_mov_b64_e32 v[78:79], v[2:3]
	v_mov_b64_e32 v[122:123], v[2:3]
	v_mov_b64_e32 v[118:119], v[2:3]
	v_mov_b64_e32 v[106:107], v[2:3]
	v_mov_b64_e32 v[102:103], v[2:3]
	v_mov_b64_e32 v[90:91], v[2:3]
	v_mov_b64_e32 v[86:87], v[2:3]
	v_mov_b64_e32 v[74:75], v[2:3]
	v_mov_b64_e32 v[70:71], v[2:3]
	v_mov_b64_e32 v[66:67], v[2:3]
	v_mov_b64_e32 v[62:63], v[2:3]
	v_mov_b64_e32 v[50:51], v[2:3]
	v_mov_b64_e32 v[46:47], v[2:3]
	v_mov_b64_e32 v[34:35], v[2:3]
	v_mov_b64_e32 v[30:31], v[2:3]
	v_mov_b64_e32 v[18:19], v[2:3]
	v_mov_b64_e32 v[10:11], v[2:3]
	v_mov_b64_e32 v[58:59], v[2:3]
	v_mov_b64_e32 v[54:55], v[2:3]
	v_mov_b64_e32 v[42:43], v[2:3]
	v_mov_b64_e32 v[38:39], v[2:3]
	v_mov_b64_e32 v[26:27], v[2:3]
	v_mov_b64_e32 v[22:23], v[2:3]
	v_mov_b64_e32 v[6:7], v[2:3]
	s_cmp_lg_u32 s35, 0
	s_cbranch_scc1 .Lg1rd_skipB
	s_waitcnt vmcnt(0)
	v_add_f32_e32 v204, v134, v135
	v_add_f32_e32 v212, v136, v137
	v_add_f32_e32 v205, v138, v139
	v_add_f32_e32 v213, v140, v141
	v_add_f32_e32 v206, v142, v143
	v_add_f32_e32 v214, v144, v145
	v_add_f32_e32 v207, v146, v147
	v_add_f32_e32 v215, v148, v149
	v_add_f32_e32 v208, v154, v155
	v_add_f32_e32 v216, v156, v157
	v_add_f32_e32 v209, v160, v161
	v_add_f32_e32 v217, v162, v163
	v_add_f32_e32 v210, v164, v165
	v_add_f32_e32 v218, v166, v167
	v_add_f32_e32 v211, v168, v169
	v_add_f32_e32 v219, v170, v171
	v_add_f32_e32 v204, v204, v212
	v_add_f32_e32 v205, v205, v213
	v_add_f32_e32 v206, v206, v214
	v_add_f32_e32 v207, v207, v215
	v_add_f32_e32 v208, v208, v216
	v_add_f32_e32 v209, v209, v217
	v_add_f32_e32 v210, v210, v218
	v_add_f32_e32 v211, v211, v219
	ds_swizzle_b32 v212, v204 offset:swizzle(SWAP,16)
	ds_swizzle_b32 v213, v205 offset:swizzle(SWAP,16)
	ds_swizzle_b32 v214, v206 offset:swizzle(SWAP,16)
	ds_swizzle_b32 v215, v207 offset:swizzle(SWAP,16)
	ds_swizzle_b32 v216, v208 offset:swizzle(SWAP,16)
	ds_swizzle_b32 v217, v209 offset:swizzle(SWAP,16)
	ds_swizzle_b32 v218, v210 offset:swizzle(SWAP,16)
	ds_swizzle_b32 v219, v211 offset:swizzle(SWAP,16)
	s_waitcnt lgkmcnt(0)
	v_add_f32_e32 v204, v204, v212
	v_add_f32_e32 v205, v205, v213
	v_add_f32_e32 v206, v206, v214
	v_add_f32_e32 v207, v207, v215
	v_add_f32_e32 v208, v208, v216
	v_add_f32_e32 v209, v209, v217
	v_add_f32_e32 v210, v210, v218
	v_add_f32_e32 v211, v211, v219
	v_mov_b32_e32 v212, v204
	v_mov_b32_e32 v213, v205
	v_mov_b32_e32 v214, v206
	v_mov_b32_e32 v215, v207
	v_mov_b32_e32 v216, v208
	v_mov_b32_e32 v217, v209
	v_mov_b32_e32 v218, v210
	v_mov_b32_e32 v219, v211
	s_nop 1
	v_permlane32_swap_b32_e32 v204, v212
	v_permlane32_swap_b32_e32 v205, v213
	v_permlane32_swap_b32_e32 v206, v214
	v_permlane32_swap_b32_e32 v207, v215
	v_permlane32_swap_b32_e32 v208, v216
	v_permlane32_swap_b32_e32 v209, v217
	v_permlane32_swap_b32_e32 v210, v218
	v_permlane32_swap_b32_e32 v211, v219
	v_add_f32_e32 v183, v204, v212
	v_add_f32_e32 v185, v205, v213
	v_add_f32_e32 v187, v206, v214
	v_add_f32_e32 v197, v207, v215
	v_add_f32_e32 v199, v208, v216
	v_add_f32_e32 v201, v209, v217
	v_add_f32_e32 v203, v210, v218
	v_add_f32_e32 v230, v211, v219
	v_fmamk_f32 v183, v183, 0x3a800000, v229
	v_fmamk_f32 v185, v185, 0x3a800000, v229
	v_fmamk_f32 v187, v187, 0x3a800000, v229
	v_fmamk_f32 v197, v197, 0x3a800000, v229
	v_fmamk_f32 v199, v199, 0x3a800000, v229
	v_fmamk_f32 v201, v201, 0x3a800000, v229
	v_fmamk_f32 v203, v203, 0x3a800000, v229
	v_fmamk_f32 v230, v230, 0x3a800000, v229
	v_rsq_f32_e32 v183, v183
	v_rsq_f32_e32 v185, v185
	v_rsq_f32_e32 v187, v187
	v_rsq_f32_e32 v197, v197
	v_rsq_f32_e32 v199, v199
	v_rsq_f32_e32 v201, v201
	v_rsq_f32_e32 v203, v203
	v_rsq_f32_e32 v230, v230
.Lg1rd_skipB:
	s_and_b64 vcc, exec, s[16:17]
	s_cbranch_vccz .LBB0_273

; __device__ __forceinline__ u32x4 pack8(const f32x4& a, const f32x4& b) { u32x4 w; w.x = cvt_pk_bf16(a[0], a[1]); w.y = cvt_pk_bf16(a[2], a[3]); w.z = cvt_pk_bf16(b[0], b[1]); w.w = cvt_pk_bf16(b[2], b[3]); return w; }
;     __device__ __forceinline__ void apply(const Ld& d, int row, int c0, int, int, int, const f32x4& a0, const f32x4& b0, const f32x4& a1, const f32x4& b1) const { half(d.g0, row, c0, a0, b0); half(d.g1, row, c0 + 128, a1, b1); }
;     __device__ __forceinline__ void apply(const Ld& d, int row, int c0, int, int, int, const f32x4& a0, const f32x4& b0, const f32x4& a1, const f32x4& b1) const { half(d.g0, d.p0, row, c0, a0, b0); half(d.g1, d.p1, row, c0 + 128, a1, b1); }
;     __device__ __forceinline__ void load(Ld& d, int row, int, int, int) const {
; #pragma unroll
;         for (int i = 0; i < 4; ++i) d.p[i] = ((const f32x4*)(ssqh + (size_t)row * 16))[i]; }
;     __device__ __forceinline__ void apply(const Ld& d, int row, int c0, int pn, int wc, int fq, const f32x4& a0, const f32x4& b0, const f32x4& a1, const f32x4& b1) const {
;         const f32x4 t = (d.p[0] + d.p[1]) + (d.p[2] + d.p[3]);
;         const float inv = __builtin_amdgcn_rsqf(((t[0] + t[1]) + (t[2] + t[3])) * (1.f / DM) + EPS);
;         const f32x4 v0 = a0 * inv, v1 = b0 * inv, v2 = a1 * inv, v3 = b1 * inv;
;         if (pn < 18) { *(u32x4*)(proj + (size_t)row * PW + c0) = pack8(v0, v1); *(u32x4*)(proj + (size_t)row * PW + c0 + 128) = pack8(v2, v3); }
;         else if (c0 < 4608 + 32) *(u32x4*)(krope + (size_t)row * 32 + (c0 - 4608)) = pack8(v0, v1);
.LBB0_295:
	s_andn2_b64 vcc, exec, s[0:1]
	s_cbranch_vccnz .LBB0_432
	s_lshl_b32 s63, s63, 8
	v_add_u32_e32 v152, s63, v17
	v_ashrrev_i32_e32 v153, 31, v152
	v_lshlrev_b64 v[158:159], 6, v[152:153]
	v_or_b32_e32 v134, 16, v152
	v_ashrrev_i32_e32 v135, 31, v134
	v_lshlrev_b64 v[134:135], 6, v[134:135]
	v_lshl_add_u64 v[146:147], s[24:25], 0, v[134:135]
	v_lshl_or_b32 v150, s71, 8, v241
	s_movk_i32 s0, 0x1220
	s_cmp_gt_i32 s71, 17
	v_cmp_gt_i32_e64 s[40:41], s0, v150
	s_cselect_b64 s[0:1], -1, 0
	s_and_b64 vcc, exec, s[0:1]
	v_mov_b32_e32 v0, v183
	s_nop 0
	v_pk_mul_f32 v[132:133], v[132:133], v[0:1] op_sel_hi:[1,0]
	v_pk_mul_f32 v[130:131], v[130:131], v[0:1] op_sel_hi:[1,0]
	v_pk_mul_f32 v[154:155], v[128:129], v[0:1] op_sel_hi:[1,0]
	v_pk_mul_f32 v[156:157], v[126:127], v[0:1] op_sel_hi:[1,0]
	s_cbranch_vccz .LBB0_309
	s_mov_b64 s[42:43], 0
	s_mov_b64 s[22:23], 0
	s_and_saveexec_b64 s[44:45], s[40:41]
	s_xor_b64 s[44:45], exec, s[44:45]
	s_cbranch_execz .LBB0_299
	v_readlane_b32 s36, v255, 22
	v_readlane_b32 s37, v255, 23
	s_mov_b64 s[22:23], exec
	v_cvt_pk_bf16_f32 v126, v130, v131
	v_cvt_pk_bf16_f32 v127, v132, v133
	v_cvt_pk_bf16_f32 v128, v156, v157
	v_cvt_pk_bf16_f32 v129, v154, v155
	s_nop 0
	v_lshl_add_u64 v[160:161], s[36:37], 0, v[158:159]

; __device__ __forceinline__ u32x4 pack8(const f32x4& a, const f32x4& b) { u32x4 w; w.x = cvt_pk_bf16(a[0], a[1]); w.y = cvt_pk_bf16(a[2], a[3]); w.z = cvt_pk_bf16(b[0], b[1]); w.w = cvt_pk_bf16(b[2], b[3]); return w; }
;     __device__ __forceinline__ void apply(const Ld& d, int row, int c0, int pn, int wc, int fq, const f32x4& a0, const f32x4& b0, const f32x4& a1, const f32x4& b1) const {
;     ...
;         const float inv = __builtin_amdgcn_rsqf(((t[0] + t[1]) + (t[2] + t[3])) * (1.f / DM) + EPS);
;         const f32x4 v0 = a0 * inv, v1 = b0 * inv, v2 = a1 * inv, v3 = b1 * inv;
;         if (pn < 18) { *(u32x4*)(proj + (size_t)row * PW + c0) = pack8(v0, v1); *(u32x4*)(proj + (size_t)row * PW + c0 + 128) = pack8(v2, v3); }
.LBB0_322:
	s_andn2_b64 vcc, exec, s[0:1]
	v_mov_b32_e32 v0, v185
	v_add_u32_e32 v118, s63, v235
	v_pk_mul_f32 v[120:121], v[112:113], v[0:1] op_sel_hi:[1,0]
	v_cndmask_b32_e64 v112, 0, 1, s[0:1]
	v_pk_mul_f32 v[116:117], v[116:117], v[0:1] op_sel_hi:[1,0]
	v_pk_mul_f32 v[114:115], v[114:115], v[0:1] op_sel_hi:[1,0]
	v_cmp_ne_u32_e64 s[42:43], 1, v112
	v_pk_mul_f32 v[122:123], v[110:111], v[0:1] op_sel_hi:[1,0]
	s_cbranch_vccnz .LBB0_326
	s_mov_b64 s[44:45], 0
	s_mov_b64 s[0:1], 0
	s_and_saveexec_b64 vcc, s[40:41]
	s_cbranch_execz .LBB0_325
	v_ashrrev_i32_e32 v119, 31, v118
	v_readlane_b32 s36, v255, 22
	v_lshlrev_b64 v[124:125], 6, v[118:119]
	v_readlane_b32 s37, v255, 23
	s_mov_b64 s[0:1], exec
	v_cvt_pk_bf16_f32 v110, v114, v115
	v_cvt_pk_bf16_f32 v111, v116, v117
	v_cvt_pk_bf16_f32 v112, v122, v123
	v_cvt_pk_bf16_f32 v113, v120, v121
	s_nop 0
	v_lshl_add_u64 v[124:125], s[36:37], 0, v[124:125]

; __device__ __forceinline__ u32x4 pack8(const f32x4& a, const f32x4& b) { u32x4 w; w.x = cvt_pk_bf16(a[0], a[1]); w.y = cvt_pk_bf16(a[2], a[3]); w.z = cvt_pk_bf16(b[0], b[1]); w.w = cvt_pk_bf16(b[2], b[3]); return w; }
;     __device__ __forceinline__ void apply(const Ld& d, int row, int c0, int pn, int wc, int fq, const f32x4& a0, const f32x4& b0, const f32x4& a1, const f32x4& b1) const {
;     ...
;         const float inv = __builtin_amdgcn_rsqf(((t[0] + t[1]) + (t[2] + t[3])) * (1.f / DM) + EPS);
;         const f32x4 v0 = a0 * inv, v1 = b0 * inv, v2 = a1 * inv, v3 = b1 * inv;
;         if (pn < 18) { *(u32x4*)(proj + (size_t)row * PW + c0) = pack8(v0, v1); *(u32x4*)(proj + (size_t)row * PW + c0 + 128) = pack8(v2, v3); }
.LBB0_339:
	v_or_b32_e32 v102, 32, v152
	v_ashrrev_i32_e32 v103, 31, v102
	v_lshlrev_b64 v[102:103], 6, v[102:103]
	v_lshl_add_u64 v[102:103], s[24:25], 0, v[102:103]
	v_or_b32_e32 v102, 48, v152
	v_ashrrev_i32_e32 v103, 31, v102
	v_lshlrev_b64 v[102:103], 6, v[102:103]
	v_lshl_add_u64 v[114:115], s[24:25], 0, v[102:103]
	s_and_b64 vcc, exec, s[42:43]
	v_mov_b32_e32 v0, v187
	v_add_u32_e32 v118, s63, v236
	v_pk_mul_f32 v[100:101], v[100:101], v[0:1] op_sel_hi:[1,0]
	v_pk_mul_f32 v[98:99], v[98:99], v[0:1] op_sel_hi:[1,0]
	v_pk_mul_f32 v[120:121], v[96:97], v[0:1] op_sel_hi:[1,0]
	v_pk_mul_f32 v[122:123], v[94:95], v[0:1] op_sel_hi:[1,0]
	s_cbranch_vccnz .LBB0_343
	s_mov_b64 s[22:23], 0
	s_mov_b64 s[0:1], 0
	s_and_saveexec_b64 vcc, s[40:41]
	s_cbranch_execz .LBB0_342
	v_ashrrev_i32_e32 v119, 31, v118
	v_readlane_b32 s36, v255, 22
	v_lshlrev_b64 v[124:125], 6, v[118:119]
	v_readlane_b32 s37, v255, 23
	s_mov_b64 s[0:1], exec
	v_cvt_pk_bf16_f32 v94, v98, v99
	v_cvt_pk_bf16_f32 v95, v100, v101
	v_cvt_pk_bf16_f32 v96, v122, v123
	v_cvt_pk_bf16_f32 v97, v120, v121
	s_nop 0
	v_lshl_add_u64 v[124:125], s[36:37], 0, v[124:125]

; __device__ __forceinline__ u32x4 pack8(const f32x4& a, const f32x4& b) { u32x4 w; w.x = cvt_pk_bf16(a[0], a[1]); w.y = cvt_pk_bf16(a[2], a[3]); w.z = cvt_pk_bf16(b[0], b[1]); w.w = cvt_pk_bf16(b[2], b[3]); return w; }
;     __device__ __forceinline__ void apply(const Ld& d, int row, int c0, int pn, int wc, int fq, const f32x4& a0, const f32x4& b0, const f32x4& a1, const f32x4& b1) const {
;     ...
;         const float inv = __builtin_amdgcn_rsqf(((t[0] + t[1]) + (t[2] + t[3])) * (1.f / DM) + EPS);
;         const f32x4 v0 = a0 * inv, v1 = b0 * inv, v2 = a1 * inv, v3 = b1 * inv;
;         if (pn < 18) { *(u32x4*)(proj + (size_t)row * PW + c0) = pack8(v0, v1); *(u32x4*)(proj + (size_t)row * PW + c0 + 128) = pack8(v2, v3); }
.LBB0_356:
	s_and_b64 vcc, exec, s[42:43]
	v_mov_b32_e32 v0, v197
	v_add_u32_e32 v86, s63, v237
	v_pk_mul_f32 v[84:85], v[84:85], v[0:1] op_sel_hi:[1,0]
	v_pk_mul_f32 v[82:83], v[82:83], v[0:1] op_sel_hi:[1,0]
	v_pk_mul_f32 v[88:89], v[80:81], v[0:1] op_sel_hi:[1,0]
	v_pk_mul_f32 v[90:91], v[78:79], v[0:1] op_sel_hi:[1,0]
	s_cbranch_vccnz .LBB0_360
	s_mov_b64 s[22:23], 0
	s_mov_b64 s[0:1], 0
	s_and_saveexec_b64 vcc, s[40:41]
	s_cbranch_execz .LBB0_359
	v_ashrrev_i32_e32 v87, 31, v86
	v_readlane_b32 s36, v255, 22
	v_lshlrev_b64 v[92:93], 6, v[86:87]
	v_readlane_b32 s37, v255, 23
	s_mov_b64 s[0:1], exec
	v_cvt_pk_bf16_f32 v78, v82, v83
	v_cvt_pk_bf16_f32 v79, v84, v85
	v_cvt_pk_bf16_f32 v80, v90, v91
	v_cvt_pk_bf16_f32 v81, v88, v89
	s_nop 0
	v_lshl_add_u64 v[92:93], s[36:37], 0, v[92:93]

; __device__ __forceinline__ u32x4 pack8(const f32x4& a, const f32x4& b) { u32x4 w; w.x = cvt_pk_bf16(a[0], a[1]); w.y = cvt_pk_bf16(a[2], a[3]); w.z = cvt_pk_bf16(b[0], b[1]); w.w = cvt_pk_bf16(b[2], b[3]); return w; }
;     __device__ __forceinline__ void apply(const Ld& d, int row, int c0, int pn, int wc, int fq, const f32x4& a0, const f32x4& b0, const f32x4& a1, const f32x4& b1) const {
;     ...
;         const float inv = __builtin_amdgcn_rsqf(((t[0] + t[1]) + (t[2] + t[3])) * (1.f / DM) + EPS);
;         const f32x4 v0 = a0 * inv, v1 = b0 * inv, v2 = a1 * inv, v3 = b1 * inv;
;         if (pn < 18) { *(u32x4*)(proj + (size_t)row * PW + c0) = pack8(v0, v1); *(u32x4*)(proj + (size_t)row * PW + c0 + 128) = pack8(v2, v3); }
.LBB0_373:
	v_add_u32_e32 v86, 0x80, v152
	v_ashrrev_i32_e32 v87, 31, v86
	v_lshlrev_b64 v[96:97], 6, v[86:87]
	v_lshl_add_u64 v[70:71], s[24:25], 0, v[96:97]
	v_add_u32_e32 v88, 0x90, v152
	v_ashrrev_i32_e32 v89, 31, v88
	v_lshlrev_b64 v[70:71], 6, v[88:89]
	v_lshl_add_u64 v[82:83], s[24:25], 0, v[70:71]
	s_and_b64 vcc, exec, s[42:43]
	v_mov_b32_e32 v0, v199
	s_nop 0
	v_pk_mul_f32 v[68:69], v[68:69], v[0:1] op_sel_hi:[1,0]
	v_pk_mul_f32 v[66:67], v[66:67], v[0:1] op_sel_hi:[1,0]
	v_pk_mul_f32 v[90:91], v[64:65], v[0:1] op_sel_hi:[1,0]
	v_pk_mul_f32 v[92:93], v[62:63], v[0:1] op_sel_hi:[1,0]
	s_cbranch_vccnz .LBB0_377
	s_mov_b64 s[22:23], 0
	s_mov_b64 s[0:1], 0
	s_and_saveexec_b64 vcc, s[40:41]
	s_cbranch_execz .LBB0_376
	v_readlane_b32 s36, v255, 22
	v_readlane_b32 s37, v255, 23
	s_mov_b64 s[0:1], exec
	v_cvt_pk_bf16_f32 v62, v66, v67
	v_cvt_pk_bf16_f32 v63, v68, v69
	v_cvt_pk_bf16_f32 v64, v92, v93
	v_cvt_pk_bf16_f32 v65, v90, v91
	s_nop 0
	v_lshl_add_u64 v[94:95], s[36:37], 0, v[96:97]

; __device__ __forceinline__ u32x4 pack8(const f32x4& a, const f32x4& b) { u32x4 w; w.x = cvt_pk_bf16(a[0], a[1]); w.y = cvt_pk_bf16(a[2], a[3]); w.z = cvt_pk_bf16(b[0], b[1]); w.w = cvt_pk_bf16(b[2], b[3]); return w; }
;     __device__ __forceinline__ void apply(const Ld& d, int row, int c0, int pn, int wc, int fq, const f32x4& a0, const f32x4& b0, const f32x4& a1, const f32x4& b1) const {
;     ...
;         const float inv = __builtin_amdgcn_rsqf(((t[0] + t[1]) + (t[2] + t[3])) * (1.f / DM) + EPS);
;         const f32x4 v0 = a0 * inv, v1 = b0 * inv, v2 = a1 * inv, v3 = b1 * inv;
;         if (pn < 18) { *(u32x4*)(proj + (size_t)row * PW + c0) = pack8(v0, v1); *(u32x4*)(proj + (size_t)row * PW + c0 + 128) = pack8(v2, v3); }
.LBB0_390:
	s_and_b64 vcc, exec, s[42:43]
	v_mov_b32_e32 v0, v201
	s_nop 0
	v_pk_mul_f32 v[52:53], v[52:53], v[0:1] op_sel_hi:[1,0]
	v_pk_mul_f32 v[50:51], v[50:51], v[0:1] op_sel_hi:[1,0]
	v_pk_mul_f32 v[54:55], v[48:49], v[0:1] op_sel_hi:[1,0]
	v_pk_mul_f32 v[56:57], v[46:47], v[0:1] op_sel_hi:[1,0]
	s_cbranch_vccnz .LBB0_394
	s_mov_b64 s[22:23], 0
	s_mov_b64 s[0:1], 0
	s_and_saveexec_b64 vcc, s[40:41]
	s_cbranch_execz .LBB0_393
	v_readlane_b32 s36, v255, 22
	v_lshlrev_b64 v[58:59], 6, v[88:89]
	v_readlane_b32 s37, v255, 23
	s_mov_b64 s[0:1], exec
	v_cvt_pk_bf16_f32 v46, v50, v51
	v_cvt_pk_bf16_f32 v47, v52, v53
	v_cvt_pk_bf16_f32 v48, v56, v57
	v_cvt_pk_bf16_f32 v49, v54, v55
	s_nop 0
	v_lshl_add_u64 v[58:59], s[36:37], 0, v[58:59]

; __device__ __forceinline__ u32x4 pack8(const f32x4& a, const f32x4& b) { u32x4 w; w.x = cvt_pk_bf16(a[0], a[1]); w.y = cvt_pk_bf16(a[2], a[3]); w.z = cvt_pk_bf16(b[0], b[1]); w.w = cvt_pk_bf16(b[2], b[3]); return w; }
;     __device__ __forceinline__ void apply(const Ld& d, int row, int c0, int pn, int wc, int fq, const f32x4& a0, const f32x4& b0, const f32x4& a1, const f32x4& b1) const {
;     ...
;         const float inv = __builtin_amdgcn_rsqf(((t[0] + t[1]) + (t[2] + t[3])) * (1.f / DM) + EPS);
;         const f32x4 v0 = a0 * inv, v1 = b0 * inv, v2 = a1 * inv, v3 = b1 * inv;
;         if (pn < 18) { *(u32x4*)(proj + (size_t)row * PW + c0) = pack8(v0, v1); *(u32x4*)(proj + (size_t)row * PW + c0 + 128) = pack8(v2, v3); }
.LBB0_407:
	v_or_b32_e32 v38, 32, v86
	v_ashrrev_i32_e32 v39, 31, v38
	v_lshlrev_b64 v[38:39], 6, v[38:39]
	v_lshl_add_u64 v[38:39], s[24:25], 0, v[38:39]
	v_or_b32_e32 v38, 48, v86
	v_ashrrev_i32_e32 v39, 31, v38
	v_lshlrev_b64 v[38:39], 6, v[38:39]
	v_lshl_add_u64 v[50:51], s[24:25], 0, v[38:39]
	s_and_b64 vcc, exec, s[42:43]
	v_mov_b32_e32 v0, v203
	v_add_u32_e32 v54, 0xa0, v152
	v_pk_mul_f32 v[36:37], v[36:37], v[0:1] op_sel_hi:[1,0]
	v_pk_mul_f32 v[34:35], v[34:35], v[0:1] op_sel_hi:[1,0]
	v_pk_mul_f32 v[56:57], v[32:33], v[0:1] op_sel_hi:[1,0]
	v_pk_mul_f32 v[58:59], v[30:31], v[0:1] op_sel_hi:[1,0]
	s_cbranch_vccnz .LBB0_411
	s_mov_b64 s[22:23], 0
	s_mov_b64 s[0:1], 0
	s_and_saveexec_b64 vcc, s[40:41]
	s_cbranch_execz .LBB0_410
	v_ashrrev_i32_e32 v55, 31, v54
	v_readlane_b32 s36, v255, 22
	v_lshlrev_b64 v[60:61], 6, v[54:55]
	v_readlane_b32 s37, v255, 23
	s_mov_b64 s[0:1], exec
	v_cvt_pk_bf16_f32 v30, v34, v35
	v_cvt_pk_bf16_f32 v31, v36, v37
	v_cvt_pk_bf16_f32 v32, v58, v59
	v_cvt_pk_bf16_f32 v33, v56, v57
	s_nop 0
	v_lshl_add_u64 v[60:61], s[36:37], 0, v[60:61]

; __device__ __forceinline__ u32x4 pack8(const f32x4& a, const f32x4& b) { u32x4 w; w.x = cvt_pk_bf16(a[0], a[1]); w.y = cvt_pk_bf16(a[2], a[3]); w.z = cvt_pk_bf16(b[0], b[1]); w.w = cvt_pk_bf16(b[2], b[3]); return w; }
;     __device__ __forceinline__ void apply(const Ld& d, int row, int c0, int pn, int wc, int fq, const f32x4& a0, const f32x4& b0, const f32x4& a1, const f32x4& b1) const {
;     ...
;         const float inv = __builtin_amdgcn_rsqf(((t[0] + t[1]) + (t[2] + t[3])) * (1.f / DM) + EPS);
;         const f32x4 v0 = a0 * inv, v1 = b0 * inv, v2 = a1 * inv, v3 = b1 * inv;
;         if (pn < 18) { *(u32x4*)(proj + (size_t)row * PW + c0) = pack8(v0, v1); *(u32x4*)(proj + (size_t)row * PW + c0 + 128) = pack8(v2, v3); }
.LBB0_424:
	s_and_b64 vcc, exec, s[42:43]
	v_mov_b32_e32 v0, v230
	v_add_u32_e32 v22, 0xb0, v152
	v_pk_mul_f32 v[20:21], v[20:21], v[0:1] op_sel_hi:[1,0]
	v_pk_mul_f32 v[18:19], v[18:19], v[0:1] op_sel_hi:[1,0]
	v_pk_mul_f32 v[24:25], v[12:13], v[0:1] op_sel_hi:[1,0]
	v_pk_mul_f32 v[26:27], v[10:11], v[0:1] op_sel_hi:[1,0]
	s_cbranch_vccnz .LBB0_428
	s_mov_b64 s[22:23], 0
	s_mov_b64 s[0:1], 0
	s_and_saveexec_b64 s[42:43], s[40:41]
	s_cbranch_execz .LBB0_427
	v_ashrrev_i32_e32 v23, 31, v22
	v_readlane_b32 s36, v255, 22
	v_lshlrev_b64 v[28:29], 6, v[22:23]
	v_readlane_b32 s37, v255, 23
	s_mov_b64 s[0:1], exec
	v_cvt_pk_bf16_f32 v10, v18, v19
	v_cvt_pk_bf16_f32 v11, v20, v21
	v_cvt_pk_bf16_f32 v12, v26, v27
	v_cvt_pk_bf16_f32 v13, v24, v25
	s_nop 0
	v_lshl_add_u64 v[28:29], s[36:37], 0, v[28:29]
